# E26: E24 + P15 attention tiles: one softmax path for FULL and masked tiles (max clamped at 0.5*NEG makes masked scores exp to exactly 0), packed subtract + packed row-sum tree
# speedup vs baseline: 1.0115x; 1.0028x over previous
.LBB0_4417:
	ds_bpermute_b32 v78, v220, v3
	v_max_f32_e32 v3, v3, v3
	s_and_b64 vcc, exec, s[90:91]
	s_waitcnt lgkmcnt(0)
	v_max_f32_e32 v78, v78, v78
	v_max_f32_e32 v3, v3, v78
	ds_bpermute_b32 v78, v221, v3
	s_waitcnt lgkmcnt(0)
	v_max3_f32 v78, v4, v3, v78
	v_max_f32_e32 v79, s97, v78
	v_pk_add_f32 v[196:197], v[196:197], v[78:79] op_sel:[0,1] op_sel_hi:[1,1] neg_lo:[0,1] neg_hi:[0,1]
	v_pk_add_f32 v[198:199], v[198:199], v[78:79] op_sel:[0,1] op_sel_hi:[1,1] neg_lo:[0,1] neg_hi:[0,1]
	v_pk_add_f32 v[200:201], v[200:201], v[78:79] op_sel:[0,1] op_sel_hi:[1,1] neg_lo:[0,1] neg_hi:[0,1]
	v_pk_add_f32 v[202:203], v[202:203], v[78:79] op_sel:[0,1] op_sel_hi:[1,1] neg_lo:[0,1] neg_hi:[0,1]
	v_pk_add_f32 v[204:205], v[204:205], v[78:79] op_sel:[0,1] op_sel_hi:[1,1] neg_lo:[0,1] neg_hi:[0,1]
	v_pk_add_f32 v[206:207], v[206:207], v[78:79] op_sel:[0,1] op_sel_hi:[1,1] neg_lo:[0,1] neg_hi:[0,1]
	v_pk_add_f32 v[208:209], v[208:209], v[78:79] op_sel:[0,1] op_sel_hi:[1,1] neg_lo:[0,1] neg_hi:[0,1]
	v_pk_add_f32 v[210:211], v[210:211], v[78:79] op_sel:[0,1] op_sel_hi:[1,1] neg_lo:[0,1] neg_hi:[0,1]
	v_exp_f32_e32 v230, v196
	v_exp_f32_e32 v231, v197
	v_exp_f32_e32 v232, v198
	v_exp_f32_e32 v234, v199
	v_exp_f32_e32 v233, v200
	v_exp_f32_e32 v235, v201
	v_exp_f32_e32 v236, v202
	v_exp_f32_e32 v237, v203
	v_exp_f32_e32 v3, v204
	v_exp_f32_e32 v103, v205
	v_exp_f32_e32 v212, v206
	v_exp_f32_e32 v224, v207
	v_exp_f32_e32 v223, v208
	v_exp_f32_e32 v225, v209
	v_exp_f32_e32 v228, v210
	v_exp_f32_e32 v229, v211
	s_nop 0
	v_pk_add_f32 v[82:83], v[224:225], v[228:229]
	v_pk_add_f32 v[84:85], v[230:231], v[232:233]
	v_pk_add_f32 v[82:83], v[82:83], v[84:85]
	v_pk_add_f32 v[84:85], v[234:235], v[236:237]
	v_pk_add_f32 v[82:83], v[82:83], v[84:85]
	v_add_f32_e32 v80, v82, v83
	v_add_f32_e32 v80, v3, v80
	v_add_f32_e32 v80, v103, v80
	v_add_f32_e32 v80, v212, v80
	v_add_f32_e32 v80, v223, v80
	s_branch .LBB0_4420

.LBB0_4423:
	ds_bpermute_b32 v62, v220, v79
	v_max_f32_e32 v63, v79, v79
	s_and_b64 vcc, exec, s[90:91]
	s_waitcnt lgkmcnt(0)
	v_max_f32_e32 v62, v62, v62
	v_max_f32_e32 v62, v63, v62
	ds_bpermute_b32 v63, v221, v62
	s_waitcnt lgkmcnt(0)
	v_max3_f32 v79, v5, v62, v63
	v_max_f32_e32 v200, s97, v79
	v_pk_add_f32 v[82:83], v[82:83], v[200:201] op_sel_hi:[1,0] neg_lo:[0,1] neg_hi:[0,1]
	v_pk_add_f32 v[84:85], v[84:85], v[200:201] op_sel_hi:[1,0] neg_lo:[0,1] neg_hi:[0,1]
	v_pk_add_f32 v[86:87], v[86:87], v[200:201] op_sel_hi:[1,0] neg_lo:[0,1] neg_hi:[0,1]
	v_pk_add_f32 v[88:89], v[88:89], v[200:201] op_sel_hi:[1,0] neg_lo:[0,1] neg_hi:[0,1]
	v_pk_add_f32 v[90:91], v[90:91], v[200:201] op_sel_hi:[1,0] neg_lo:[0,1] neg_hi:[0,1]
	v_pk_add_f32 v[92:93], v[92:93], v[200:201] op_sel_hi:[1,0] neg_lo:[0,1] neg_hi:[0,1]
	v_pk_add_f32 v[196:197], v[196:197], v[200:201] op_sel_hi:[1,0] neg_lo:[0,1] neg_hi:[0,1]
	v_pk_add_f32 v[198:199], v[198:199], v[200:201] op_sel_hi:[1,0] neg_lo:[0,1] neg_hi:[0,1]
	v_exp_f32_e32 v70, v82
	v_exp_f32_e32 v71, v83
	v_exp_f32_e32 v72, v84
	v_exp_f32_e32 v74, v85
	v_exp_f32_e32 v73, v86
	v_exp_f32_e32 v75, v87
	v_exp_f32_e32 v76, v88
	v_exp_f32_e32 v77, v89
	v_exp_f32_e32 v62, v90
	v_exp_f32_e32 v63, v91
	v_exp_f32_e32 v64, v92
	v_exp_f32_e32 v66, v93
	v_exp_f32_e32 v65, v196
	v_exp_f32_e32 v67, v197
	v_exp_f32_e32 v68, v198
	v_exp_f32_e32 v69, v199
	s_nop 0
	v_pk_add_f32 v[82:83], v[62:63], v[64:65]
	v_pk_add_f32 v[84:85], v[66:67], v[68:69]
	v_pk_add_f32 v[82:83], v[82:83], v[84:85]
	v_pk_add_f32 v[84:85], v[70:71], v[72:73]
	v_pk_add_f32 v[82:83], v[82:83], v[84:85]
	v_pk_add_f32 v[84:85], v[74:75], v[76:77]
	v_pk_add_f32 v[82:83], v[82:83], v[84:85]
	v_add_f32_e32 v81, v82, v83
	s_branch .LBB0_4426

.LBB0_4447:
	ds_bpermute_b32 v3, v220, v103
	v_max_f32_e32 v78, v103, v103
	s_and_b64 vcc, exec, s[38:39]
	s_waitcnt lgkmcnt(0)
	v_max_f32_e32 v3, v3, v3
	v_max_f32_e32 v3, v78, v3
	ds_bpermute_b32 v78, v221, v3
	s_waitcnt lgkmcnt(0)
	v_max3_f32 v78, v4, v3, v78
	v_max_f32_e32 v79, s97, v78
	v_sub_f32_e32 v3, v90, v79
	v_pk_add_f32 v[196:197], v[196:197], v[78:79] op_sel:[0,1] op_sel_hi:[1,1] neg_lo:[0,1] neg_hi:[0,1]
	v_sub_f32_e32 v81, v93, v79
	v_pk_add_f32 v[198:199], v[198:199], v[78:79] op_sel:[0,1] op_sel_hi:[1,1] neg_lo:[0,1] neg_hi:[0,1]
	v_pk_add_f32 v[200:201], v[200:201], v[78:79] op_sel:[0,1] op_sel_hi:[1,1] neg_lo:[0,1] neg_hi:[0,1]
	v_pk_add_f32 v[202:203], v[202:203], v[78:79] op_sel:[0,1] op_sel_hi:[1,1] neg_lo:[0,1] neg_hi:[0,1]
	v_pk_add_f32 v[204:205], v[204:205], v[78:79] op_sel:[0,1] op_sel_hi:[1,1] neg_lo:[0,1] neg_hi:[0,1]
	v_pk_add_f32 v[206:207], v[206:207], v[78:79] op_sel:[0,1] op_sel_hi:[1,1] neg_lo:[0,1] neg_hi:[0,1]
	v_pk_add_f32 v[208:209], v[208:209], v[78:79] op_sel:[0,1] op_sel_hi:[1,1] neg_lo:[0,1] neg_hi:[0,1]
	v_exp_f32_e32 v228, v3
	v_exp_f32_e32 v229, v196
	v_exp_f32_e32 v230, v197
	v_exp_f32_e32 v232, v81
	v_exp_f32_e32 v231, v198
	v_exp_f32_e32 v233, v199
	v_exp_f32_e32 v234, v200
	v_exp_f32_e32 v235, v201
	v_exp_f32_e32 v3, v202
	v_exp_f32_e32 v103, v203
	v_exp_f32_e32 v210, v204
	v_exp_f32_e32 v212, v205
	v_exp_f32_e32 v211, v206
	v_exp_f32_e32 v223, v207
	v_exp_f32_e32 v224, v208
	v_exp_f32_e32 v225, v209
	s_nop 0
	v_pk_add_f32 v[82:83], v[210:211], v[224:225]
	v_pk_add_f32 v[84:85], v[228:229], v[230:231]
	v_pk_add_f32 v[82:83], v[82:83], v[84:85]
	v_pk_add_f32 v[84:85], v[232:233], v[234:235]
	v_pk_add_f32 v[82:83], v[82:83], v[84:85]
	v_add_f32_e32 v80, v82, v83
	v_add_f32_e32 v80, v3, v80
	v_add_f32_e32 v80, v103, v80
	v_add_f32_e32 v80, v212, v80
	v_add_f32_e32 v80, v223, v80
	s_branch .LBB0_4450

.LBB0_4453:
	ds_bpermute_b32 v62, v220, v81
	v_max_f32_e32 v63, v81, v81
	s_and_b64 vcc, exec, s[38:39]
	s_waitcnt lgkmcnt(0)
	v_max_f32_e32 v62, v62, v62
	v_max_f32_e32 v62, v63, v62
	ds_bpermute_b32 v63, v221, v62
	s_waitcnt lgkmcnt(0)
	v_max3_f32 v79, v5, v62, v63
	v_max_f32_e32 v200, s97, v79
	v_sub_f32_e32 v62, v74, v200
	v_pk_add_f32 v[82:83], v[82:83], v[200:201] op_sel_hi:[1,0] neg_lo:[0,1] neg_hi:[0,1]
	v_sub_f32_e32 v65, v77, v200
	v_pk_add_f32 v[84:85], v[84:85], v[200:201] op_sel_hi:[1,0] neg_lo:[0,1] neg_hi:[0,1]
	v_pk_add_f32 v[86:87], v[86:87], v[200:201] op_sel_hi:[1,0] neg_lo:[0,1] neg_hi:[0,1]
	v_pk_add_f32 v[88:89], v[88:89], v[200:201] op_sel_hi:[1,0] neg_lo:[0,1] neg_hi:[0,1]
	v_pk_add_f32 v[90:91], v[90:91], v[200:201] op_sel_hi:[1,0] neg_lo:[0,1] neg_hi:[0,1]
	v_pk_add_f32 v[92:93], v[92:93], v[200:201] op_sel_hi:[1,0] neg_lo:[0,1] neg_hi:[0,1]
	v_pk_add_f32 v[196:197], v[196:197], v[200:201] op_sel_hi:[1,0] neg_lo:[0,1] neg_hi:[0,1]
	v_exp_f32_e32 v70, v62
	v_exp_f32_e32 v71, v82
	v_exp_f32_e32 v72, v83
	v_exp_f32_e32 v75, v65
	v_exp_f32_e32 v73, v84
	v_exp_f32_e32 v76, v85
	v_exp_f32_e32 v198, v86
	v_exp_f32_e32 v199, v87
	v_exp_f32_e32 v62, v88
	v_exp_f32_e32 v63, v89
	v_exp_f32_e32 v64, v90
	v_exp_f32_e32 v66, v91
	v_exp_f32_e32 v65, v92
	v_exp_f32_e32 v67, v93
	v_exp_f32_e32 v68, v196
	v_exp_f32_e32 v69, v197
	s_nop 0
	v_pk_add_f32 v[82:83], v[62:63], v[64:65]
	v_pk_add_f32 v[84:85], v[66:67], v[68:69]
	v_pk_add_f32 v[82:83], v[82:83], v[84:85]
	v_pk_add_f32 v[84:85], v[70:71], v[72:73]
	v_pk_add_f32 v[82:83], v[82:83], v[84:85]
	v_pk_add_f32 v[82:83], v[82:83], v[198:199]
	v_add_f32_e32 v81, v82, v83
	v_add_f32_e32 v81, v75, v81
	v_add_f32_e32 v81, v76, v81
	s_branch .LBB0_4456
